# rec_pass1 last segment: the heavy wave of each SIMD pair (w >= 2 key blocks) runs at s_setprio 2, reset at the item-loop increment
# baseline (speedup 1.0000x reference)
.LBB0_189:
	s_setprio 0
	s_add_i32 s20, s20, s72
	s_add_i32 s9, s9, s10
	s_cmpk_gt_i32 s20, 0x4ff
	s_cbranch_scc1 .LBB0_305

.LBB0_196:
	s_or_b64 exec, exec, s[2:3]
	v_mul_u32_u24_e32 v4, 0x84, v114
	v_add3_u32 v6, v105, v104, v4
	ds_read2_b32 v[228:229], v6 offset1:33
	ds_read2_b32 v[230:231], v6 offset0:66 offset1:99
	ds_read2_b32 v[232:233], v6 offset0:132 offset1:165
	ds_read2_b32 v[234:235], v6 offset0:198 offset1:231
	s_movk_i32 s2, 0x90
	v_bfe_u32 v7, v111, 5, 3
	v_lshlrev_b32_e32 v8, 4, v7
	v_mul_u32_u24_e32 v7, 0x420, v7
	v_lshlrev_b32_e32 v15, 3, v112
	s_waitcnt lgkmcnt(0)
	v_pk_add_f32 v[228:229], v[106:107], v[228:229] op_sel_hi:[0,1]
	v_pk_add_f32 v[230:231], v[106:107], v[230:231] op_sel_hi:[0,1]
	v_pk_add_f32 v[232:233], v[106:107], v[232:233] op_sel_hi:[0,1]
	v_pk_add_f32 v[234:235], v[106:107], v[234:235] op_sel_hi:[0,1]
	ds_write2_b32 v6, v228, v229 offset1:33
	ds_write2_b32 v6, v230, v231 offset0:66 offset1:99
	ds_write2_b32 v6, v232, v233 offset0:132 offset1:165
	ds_write2_b32 v6, v234, v235 offset0:198 offset1:231
	v_and_b32_e32 v5, 31, v111
	v_lshlrev_b32_e32 v6, 2, v5
	v_add_u32_e32 v4, v105, v6
	s_waitcnt lgkmcnt(0)
	s_barrier
	ds_read_b32 v4, v4 offset:8316
	v_mad_u32_u24 v5, v5, s2, v105
	s_mov_b32 s2, 0xac00
	v_add3_u32 v5, v5, v8, s2
	v_add3_u32 v6, v105, v7, v6
	v_add_u32_e32 v199, 0x210, v6
	v_add_u32_e32 v200, 0x4400, v6
	v_add_u32_e32 v201, 0x4610, v6
	ds_read2_b32 v[236:237], v200 offset1:33
	ds_read2_b32 v[238:239], v6 offset1:33
	ds_read2_b32 v[240:241], v200 offset0:66 offset1:99
	ds_read2_b32 v[242:243], v6 offset0:66 offset1:99
	ds_read2_b32 v[244:245], v201 offset1:33
	ds_read2_b32 v[246:247], v199 offset1:33
	ds_read2_b32 v[248:249], v201 offset0:66 offset1:99
	ds_read2_b32 v[250:251], v199 offset0:66 offset1:99
	s_waitcnt lgkmcnt(0)
	v_sub_f32_e32 v238, v4, v238
	v_sub_f32_e32 v239, v4, v239
	v_sub_f32_e32 v242, v4, v242
	v_sub_f32_e32 v243, v4, v243
	v_mul_f32_e32 v238, 0x3fb8aa3b, v238
	v_mul_f32_e32 v239, 0x3fb8aa3b, v239
	v_mul_f32_e32 v242, 0x3fb8aa3b, v242
	v_mul_f32_e32 v243, 0x3fb8aa3b, v243
	v_exp_f32_e32 v238, v238
	v_exp_f32_e32 v239, v239
	v_exp_f32_e32 v242, v242
	v_exp_f32_e32 v243, v243
	s_nop 0
	v_mul_f32_e32 v238, v236, v238
	v_mul_f32_e32 v239, v237, v239
	v_mul_f32_e32 v242, v240, v242
	v_mul_f32_e32 v243, v241, v243
	v_cvt_pk_bf16_f32 v236, v238, v239
	v_cvt_pk_bf16_f32 v237, v242, v243
	ds_write_b64 v5, v[236:237]
	v_sub_f32_e32 v246, v4, v246
	v_sub_f32_e32 v247, v4, v247
	v_sub_f32_e32 v250, v4, v250
	v_sub_f32_e32 v251, v4, v251
	v_mul_f32_e32 v246, 0x3fb8aa3b, v246
	v_mul_f32_e32 v247, 0x3fb8aa3b, v247
	v_mul_f32_e32 v250, 0x3fb8aa3b, v250
	v_mul_f32_e32 v251, 0x3fb8aa3b, v251
	v_exp_f32_e32 v246, v246
	v_exp_f32_e32 v247, v247
	v_exp_f32_e32 v250, v250
	v_exp_f32_e32 v251, v251
	s_nop 0
	v_mul_f32_e32 v246, v244, v246
	v_mul_f32_e32 v247, v245, v247
	v_mul_f32_e32 v250, v248, v250
	v_mul_f32_e32 v251, v249, v251
	v_cvt_pk_bf16_f32 v244, v246, v247
	v_cvt_pk_bf16_f32 v245, v250, v251
	ds_write_b64 v5, v[244:245] offset:8
	v_lshl_add_u32 v8, v15, 1, v105
	s_movk_i32 s2, 0x90
	v_mad_u32_u24 v12, v110, s2, v8
	s_waitcnt lgkmcnt(0)
	s_barrier
	v_readfirstlane_b32 s100, v206
	s_nop 3
	s_lshr_b32 s100, s100, 6
	s_sub_i32 s101, 7, s100
	s_cmp_lt_u32 s100, 4
	s_cselect_b32 s100, s100, s101
	s_cmp_lt_u32 s100, 2
	s_cbranch_scc1 .Lhprio_g
	s_setprio 2
.Lhprio_g:
	ds_read_b128 v[4:7], v12 offset:34816
	v_mad_u32_u24 v13, v107, s2, v8
	ds_read_b128 v[8:11], v13 offset:44032
	ds_read_b128 v[16:19], v13 offset:46336
	ds_read_b128 v[20:23], v12 offset:34880
	ds_read_b128 v[24:27], v13 offset:46400
	s_waitcnt lgkmcnt(3)
	v_mfma_f32_16x16x32_bf16 v[8:11], v[8:11], v[4:7], 0
	v_ashrrev_i32_e32 v103, 31, v102
	v_readlane_b32 s2, v254, 17
	v_readlane_b32 s3, v254, 18
	s_waitcnt lgkmcnt(2)
	v_mfma_f32_16x16x32_bf16 v[4:7], v[16:19], v[4:7], 0
	ds_read_b128 v[16:19], v13 offset:44096
	v_mov_b32_e32 v13, v177
	v_cmp_lt_u32_sdwa s[4:5], v111, v218 src0_sel:BYTE_0 src1_sel:DWORD
	s_waitcnt lgkmcnt(1)
	v_mfma_f32_16x16x32_bf16 v[4:7], v[24:27], v[20:23], v[4:7]
	v_lshlrev_b32_e32 v24, 2, v112
	s_waitcnt lgkmcnt(0)
	v_mfma_f32_16x16x32_bf16 v[16:19], v[16:19], v[20:23], v[8:11]
	s_nop 2
	v_or_b32_e32 v198, v113, v107
	v_lshl_or_b32 v198, v198, 5, v24
	v_lshlrev_b32_e32 v196, 2, v198
	v_mov_b32_e32 v197, v177
	v_or_b32_e32 v11, v113, v24
	v_lshlrev_b32_e32 v11, 5, v11
	v_lshlrev_b64 v[8:9], 13, v[102:103]
	v_or_b32_e32 v12, v11, v107
	v_lshl_add_u64 v[8:9], s[2:3], 0, v[8:9]
	v_lshl_add_u64 v[196:197], v[8:9], 0, v[196:197]
	v_lshlrev_b32_e32 v12, 2, v12
	v_or_b32_e32 v10, 16, v107
	v_lshl_add_u64 v[12:13], v[8:9], 0, v[12:13]
	global_store_dwordx4 v[196:197], v[16:19], off sc1
	global_store_dwordx4 v[196:197], v[4:7], off offset:64 sc1
	s_nop 1
	v_or_b32_e32 v4, v11, v10
	v_lshlrev_b32_e32 v12, 2, v4
	v_mov_b32_e32 v13, v177
	v_lshl_add_u64 v[8:9], v[8:9], 0, v[12:13]
	s_and_saveexec_b64 s[2:3], s[4:5]
	s_cbranch_execz .LBB0_200
	v_lshlrev_b32_sdwa v4, v213, v111 dst_sel:DWORD dst_unused:UNUSED_PAD src0_sel:DWORD src1_sel:BYTE_0
	v_add_u32_e32 v5, v105, v4
	ds_read_b32 v5, v5 offset:8316
	v_readlane_b32 s4, v254, 19
	v_lshlrev_b64 v[6:7], 7, v[102:103]
	v_readlane_b32 s5, v254, 20
	s_waitcnt lgkmcnt(0)
	v_mul_f32_e32 v5, 0x3fb8aa3b, v5
	v_exp_f32_e32 v8, v5
	v_lshl_add_u64 v[6:7], s[4:5], 0, v[6:7]
	v_mov_b32_e32 v5, v177
	v_lshl_add_u64 v[4:5], v[6:7], 0, v[4:5]
	global_store_dword v[4:5], v8, off

.LBB0_238:
	s_or_b64 exec, exec, s[2:3]
	v_lshlrev_b32_e32 v29, 3, v23
	v_lshl_add_u32 v8, v21, 2, v28
	v_mov_b32_e32 v21, v20
	v_mad_u32_u24 v30, v18, s14, v8
	ds_read_b32 v80, v30
	ds_read_b32 v81, v30 offset:260
	ds_read_b32 v82, v30 offset:520
	ds_read_b32 v83, v30 offset:780
	ds_read_b32 v84, v30 offset:1040
	ds_read_b32 v85, v30 offset:1300
	ds_read_b32 v86, v30 offset:1560
	ds_read_b32 v87, v30 offset:1820
	ds_read_b32 v88, v30 offset:2080
	ds_read_b32 v89, v30 offset:2340
	ds_read_b32 v90, v30 offset:2600
	ds_read_b32 v91, v30 offset:2860
	ds_read_b32 v92, v30 offset:3120
	ds_read_b32 v93, v30 offset:3380
	ds_read_b32 v94, v30 offset:3640
	ds_read_b32 v95, v30 offset:3900
	s_waitcnt lgkmcnt(0)
	v_add_f32_e32 v80, v20, v80
	v_add_f32_e32 v81, v20, v81
	v_add_f32_e32 v82, v20, v82
	v_add_f32_e32 v83, v20, v83
	v_add_f32_e32 v84, v20, v84
	v_add_f32_e32 v85, v20, v85
	v_add_f32_e32 v86, v20, v86
	v_add_f32_e32 v87, v20, v87
	v_add_f32_e32 v88, v20, v88
	v_add_f32_e32 v89, v20, v89
	v_add_f32_e32 v90, v20, v90
	v_add_f32_e32 v91, v20, v91
	v_add_f32_e32 v92, v20, v92
	v_add_f32_e32 v93, v20, v93
	v_add_f32_e32 v94, v20, v94
	v_add_f32_e32 v95, v20, v95
	ds_write_b32 v30, v80
	ds_write_b32 v30, v81 offset:260
	ds_write_b32 v30, v82 offset:520
	ds_write_b32 v30, v83 offset:780
	ds_write_b32 v30, v84 offset:1040
	ds_write_b32 v30, v85 offset:1300
	ds_write_b32 v30, v86 offset:1560
	ds_write_b32 v30, v87 offset:1820
	ds_write_b32 v30, v88 offset:2080
	ds_write_b32 v30, v89 offset:2340
	ds_write_b32 v30, v90 offset:2600
	ds_write_b32 v30, v91 offset:2860
	ds_write_b32 v30, v92 offset:3120
	ds_write_b32 v30, v93 offset:3380
	ds_write_b32 v30, v94 offset:3640
	ds_write_b32 v30, v95 offset:3900
	v_and_b32_e32 v9, 63, v22
	v_lshlrev_b32_e32 v10, 2, v9
	v_add_u32_e32 v8, v28, v10
	s_waitcnt lgkmcnt(0)
	s_barrier
	ds_read_b32 v8, v8 offset:16380
	s_movk_i32 s2, 0x90
	v_mad_u32_u24 v9, v9, s2, v28
	v_lshlrev_b32_e32 v11, 5, v17
	s_mov_b32 s2, 0xac00
	v_add3_u32 v9, v9, v11, s2
	v_mul_u32_u24_e32 v11, 0x1040, v17
	v_add3_u32 v10, v28, v11, v10
	v_add_u32_e32 v72, 0x410, v10
	v_add_u32_e32 v73, 0x820, v10
	v_add_u32_e32 v74, 0xc30, v10
	v_add_u32_e32 v76, 0x4400, v10
	v_add_u32_e32 v77, 0x4810, v10
	v_add_u32_e32 v78, 0x4c20, v10
	v_add_u32_e32 v79, 0x5030, v10
	ds_read2_b32 v[96:97], v76 offset1:65
	ds_read2_b32 v[98:99], v10 offset1:65
	ds_read2_b32 v[100:101], v76 offset0:130 offset1:195
	ds_read2_b32 v[102:103], v10 offset0:130 offset1:195
	ds_read2_b32 v[104:105], v77 offset1:65
	ds_read2_b32 v[106:107], v72 offset1:65
	ds_read2_b32 v[108:109], v77 offset0:130 offset1:195
	ds_read2_b32 v[110:111], v72 offset0:130 offset1:195
	ds_read2_b32 v[112:113], v78 offset1:65
	ds_read2_b32 v[114:115], v73 offset1:65
	ds_read2_b32 v[116:117], v78 offset0:130 offset1:195
	ds_read2_b32 v[118:119], v73 offset0:130 offset1:195
	ds_read2_b32 v[120:121], v79 offset1:65
	ds_read2_b32 v[122:123], v74 offset1:65
	ds_read2_b32 v[124:125], v79 offset0:130 offset1:195
	ds_read2_b32 v[126:127], v74 offset0:130 offset1:195
	s_waitcnt lgkmcnt(0)
	v_sub_f32_e32 v98, v8, v98
	v_sub_f32_e32 v99, v8, v99
	v_sub_f32_e32 v102, v8, v102
	v_sub_f32_e32 v103, v8, v103
	v_mul_f32_e32 v98, 0x3fb8aa3b, v98
	v_mul_f32_e32 v99, 0x3fb8aa3b, v99
	v_mul_f32_e32 v102, 0x3fb8aa3b, v102
	v_mul_f32_e32 v103, 0x3fb8aa3b, v103
	v_exp_f32_e32 v98, v98
	v_exp_f32_e32 v99, v99
	v_exp_f32_e32 v102, v102
	v_exp_f32_e32 v103, v103
	s_nop 0
	v_mul_f32_e32 v98, v96, v98
	v_mul_f32_e32 v99, v97, v99
	v_mul_f32_e32 v102, v100, v102
	v_mul_f32_e32 v103, v101, v103
	v_cvt_pk_bf16_f32 v96, v98, v99
	v_cvt_pk_bf16_f32 v97, v102, v103
	ds_write_b64 v9, v[96:97]
	v_sub_f32_e32 v106, v8, v106
	v_sub_f32_e32 v107, v8, v107
	v_sub_f32_e32 v110, v8, v110
	v_sub_f32_e32 v111, v8, v111
	v_mul_f32_e32 v106, 0x3fb8aa3b, v106
	v_mul_f32_e32 v107, 0x3fb8aa3b, v107
	v_mul_f32_e32 v110, 0x3fb8aa3b, v110
	v_mul_f32_e32 v111, 0x3fb8aa3b, v111
	v_exp_f32_e32 v106, v106
	v_exp_f32_e32 v107, v107
	v_exp_f32_e32 v110, v110
	v_exp_f32_e32 v111, v111
	s_nop 0
	v_mul_f32_e32 v106, v104, v106
	v_mul_f32_e32 v107, v105, v107
	v_mul_f32_e32 v110, v108, v110
	v_mul_f32_e32 v111, v109, v111
	v_cvt_pk_bf16_f32 v104, v106, v107
	v_cvt_pk_bf16_f32 v105, v110, v111
	ds_write_b64 v9, v[104:105] offset:8
	v_sub_f32_e32 v114, v8, v114
	v_sub_f32_e32 v115, v8, v115
	v_sub_f32_e32 v118, v8, v118
	v_sub_f32_e32 v119, v8, v119
	v_mul_f32_e32 v114, 0x3fb8aa3b, v114
	v_mul_f32_e32 v115, 0x3fb8aa3b, v115
	v_mul_f32_e32 v118, 0x3fb8aa3b, v118
	v_mul_f32_e32 v119, 0x3fb8aa3b, v119
	v_exp_f32_e32 v114, v114
	v_exp_f32_e32 v115, v115
	v_exp_f32_e32 v118, v118
	v_exp_f32_e32 v119, v119
	s_nop 0
	v_mul_f32_e32 v114, v112, v114
	v_mul_f32_e32 v115, v113, v115
	v_mul_f32_e32 v118, v116, v118
	v_mul_f32_e32 v119, v117, v119
	v_cvt_pk_bf16_f32 v112, v114, v115
	v_cvt_pk_bf16_f32 v113, v118, v119
	ds_write_b64 v9, v[112:113] offset:16
	v_sub_f32_e32 v122, v8, v122
	v_sub_f32_e32 v123, v8, v123
	v_sub_f32_e32 v126, v8, v126
	v_sub_f32_e32 v127, v8, v127
	v_mul_f32_e32 v122, 0x3fb8aa3b, v122
	v_mul_f32_e32 v123, 0x3fb8aa3b, v123
	v_mul_f32_e32 v126, 0x3fb8aa3b, v126
	v_mul_f32_e32 v127, 0x3fb8aa3b, v127
	v_exp_f32_e32 v122, v122
	v_exp_f32_e32 v123, v123
	v_exp_f32_e32 v126, v126
	v_exp_f32_e32 v127, v127
	s_nop 0
	v_mul_f32_e32 v122, v120, v122
	v_mul_f32_e32 v123, v121, v123
	v_mul_f32_e32 v126, v124, v126
	v_mul_f32_e32 v127, v125, v127
	v_cvt_pk_bf16_f32 v120, v122, v123
	v_cvt_pk_bf16_f32 v121, v126, v127
	ds_write_b64 v9, v[120:121] offset:24
	v_lshl_add_u32 v12, v29, 1, v28
	s_movk_i32 s2, 0x90
	v_mad_u32_u24 v17, v19, s2, v12
	s_waitcnt lgkmcnt(0)
	s_barrier
	v_readfirstlane_b32 s100, v206
	s_nop 3
	s_lshr_b32 s100, s100, 6
	s_sub_i32 s101, 7, s100
	s_cmp_lt_u32 s100, 4
	s_cselect_b32 s100, s100, s101
	s_cmp_lt_u32 s100, 2
	s_cbranch_scc1 .Lhprio_h
	s_setprio 2
.Lhprio_h:
	ds_read_b128 v[8:11], v17 offset:34816
	v_mad_u32_u24 v18, v26, s2, v12
	ds_read_b128 v[12:15], v18 offset:44032
	ds_read_b128 v[34:37], v18 offset:46336
	ds_read_b128 v[38:41], v18 offset:48640
	ds_read_b128 v[42:45], v18 offset:50944
	s_waitcnt lgkmcnt(3)
	v_mfma_f32_16x16x32_bf16 v[12:15], v[12:15], v[8:11], 0
	v_lshlrev_b32_e32 v30, 2, v23
	v_mov_b32_e32 v33, v177
	v_or_b32_e32 v51, 16, v26
	s_waitcnt lgkmcnt(2)
	v_mfma_f32_16x16x32_bf16 v[34:37], v[34:37], v[8:11], 0
	v_or_b32_e32 v48, 32, v26
	v_or_b32_e32 v31, 48, v26
	v_cmp_lt_u32_sdwa s[4:5], v22, v216 src0_sel:BYTE_0 src1_sel:DWORD
	s_waitcnt lgkmcnt(1)
	v_mfma_f32_16x16x32_bf16 v[38:41], v[38:41], v[8:11], 0
	s_waitcnt lgkmcnt(0)
	v_mfma_f32_16x16x32_bf16 v[8:11], v[42:45], v[8:11], 0
	ds_read_b128 v[42:45], v17 offset:34880
	ds_read_b128 v[52:55], v18 offset:44096
	v_ashrrev_i32_e32 v17, 31, v16
	v_lshlrev_b64 v[20:21], 14, v[16:17]
	s_waitcnt lgkmcnt(0)
	v_mfma_f32_16x16x32_bf16 v[12:15], v[52:55], v[42:45], v[12:15]
	ds_read_b128 v[52:55], v18 offset:46400
	v_lshl_add_u64 v[20:21], s[78:79], 0, v[20:21]
	s_waitcnt lgkmcnt(0)
	v_mfma_f32_16x16x32_bf16 v[34:37], v[52:55], v[42:45], v[34:37]
	ds_read_b128 v[52:55], v18 offset:48704
	s_waitcnt lgkmcnt(0)
	v_mfma_f32_16x16x32_bf16 v[38:41], v[52:55], v[42:45], v[38:41]
	ds_read_b128 v[52:55], v18 offset:51008
	v_or_b32_e32 v66, v32, v26
	v_lshl_or_b32 v66, v66, 6, v30
	v_lshlrev_b32_e32 v66, 2, v66
	v_mov_b32_e32 v67, v177
	v_lshl_add_u64 v[66:67], v[20:21], 0, v[66:67]
	v_or_b32_e32 v18, v32, v30
	v_lshlrev_b32_e32 v18, 6, v18
	v_or_b32_e32 v23, v18, v26
	v_lshlrev_b32_e32 v32, 2, v23
	v_lshl_add_u64 v[32:33], v[20:21], 0, v[32:33]
	global_store_dwordx4 v[66:67], v[12:15], off sc1
	global_store_dwordx4 v[66:67], v[34:37], off offset:64 sc1
	global_store_dwordx4 v[66:67], v[38:41], off offset:128 sc1
	s_nop 1
	v_or_b32_e32 v12, v18, v51
	v_lshlrev_b32_e32 v12, 2, v12
	v_mov_b32_e32 v13, v177
	v_lshl_add_u64 v[12:13], v[20:21], 0, v[12:13]
	v_or_b32_e32 v12, v18, v48
	v_lshlrev_b32_e32 v12, 2, v12
	v_mov_b32_e32 v13, v177
	s_waitcnt lgkmcnt(0)
	v_mfma_f32_16x16x32_bf16 v[8:11], v[52:55], v[42:45], v[8:11]
	v_lshl_add_u64 v[12:13], v[20:21], 0, v[12:13]
	s_nop 3
	s_nop 3
	global_store_dwordx4 v[66:67], v[8:11], off offset:192 sc1
	s_nop 1
	v_or_b32_e32 v8, v18, v31
	v_lshlrev_b32_e32 v12, 2, v8
	v_mov_b32_e32 v13, v177
	v_lshl_add_u64 v[12:13], v[20:21], 0, v[12:13]
	s_and_saveexec_b64 s[2:3], s[4:5]
	s_cbranch_execz .LBB0_244
	v_lshlrev_b32_sdwa v8, v213, v22 dst_sel:DWORD dst_unused:UNUSED_PAD src0_sel:DWORD src1_sel:BYTE_0
	v_add_u32_e32 v9, v28, v8
	ds_read_b32 v9, v9 offset:16380
	v_readlane_b32 s4, v254, 21
	v_lshlrev_b64 v[10:11], 8, v[16:17]
	v_readlane_b32 s5, v254, 22
	s_waitcnt lgkmcnt(0)
	v_mul_f32_e32 v9, 0x3fb8aa3b, v9
	v_exp_f32_e32 v12, v9
	v_lshl_add_u64 v[10:11], s[4:5], 0, v[10:11]
	v_mov_b32_e32 v9, v177
	v_lshl_add_u64 v[8:9], v[10:11], 0, v[8:9]
	global_store_dword v[8:9], v12, off
